# attention: 4-slot DMA ring, waves 0-3 take the per-half-trip barrier before the VALU window and waves 4-7 after it (phase offset, no tile lag); nt x stores
# speedup vs baseline: 1.0032x; 1.0032x over previous
; __device__ __forceinline__ void finishSM(f32x16& p0, f32x16& p1, float alpha, float& l_reg, bf16x8& pa0, bf16x8& pa1, bf16x8& pa2, bf16x8& pa3) {
;   for (int r = 0; r < 16; ++r) p1[r] = __builtin_amdgcn_exp2f(p1[r]);
;   float ps = 0; for (int r = 0; r < 16; ++r) ps += p0[r]; for (int r = 0; r < 16; ++r) ps += p1[r];
;   { auto rr = __builtin_amdgcn_permlane32_swap(__float_as_uint(ps), __float_as_uint(ps), false, false);
;     ps = __uint_as_float(rr[0]) + __uint_as_float(rr[1]); }
;   l_reg = l_reg * alpha + ps;
;     ...
;   PK4(p0, 0, pa0); PK4(p0, 8, pa1); PK4(p1, 0, pa2); PK4(p1, 8, pa3);
;     ...
; }
; __device__ __forceinline__ void qkt(f32x16& p0, f32x16& p1, const bf16* Ks, const bf16x8* qr, int r32, int hi) {
;   p0 = f32x16{}; p1 = f32x16{};
;   for (int d0 = 0; d0 < 8; ++d0) { int cb = (d0 * 16 + hi * 8) * 2;
;     bf16x8 b0 = *reinterpret_cast<const bf16x8*>((const char*)Ks + KSWZ(r32, cb));
;     bf16x8 b1 = *reinterpret_cast<const bf16x8*>((const char*)Ks + KSWZ(32 + r32, cb));
;     p0 = __builtin_amdgcn_mfma_f32_32x32x16_bf16(b0, qr[d0], p0, 0, 0, 0);
;     p1 = __builtin_amdgcn_mfma_f32_32x32x16_bf16(b1, qr[d0], p1, 0, 0, 0); }
; }
; __device__ __forceinline__ int v_st(int k, int c) { const int kk = (k & ~0xC) | ((k & 4) << 1) | ((k & 8) >> 1); return ((kk >> 3) * 4 + (c >> 5)) * 512 + ((kk & 7) * 32 + (c & 31)) * 2; }
; __device__ __forceinline__ int v_rd_base(int lane) { return ((lane & 3) << 3) | (((lane >> 2) & 3) << 6) | (((lane >> 4) & 1) << 5) | (((lane >> 5) & 1) << 8); }
; template <int OFF> __device__ __forceinline__ s16x4 tr_read(int vb) {
;   s16x4 r; asm volatile("ds_read_b64_tr_b16 %0, %1 offset:%2" : "=&v"(r) : "v"(vb), "i"(OFF) : "memory"); return r;
; }
; template <int D0> __device__ __forceinline__ void pv_one(f32x16& od, int vb, bf16x8 pa0, bf16x8 pa1, bf16x8 pa2, bf16x8 pa3) {
;   const s16x4 l0 = tr_read<v_rd_off(D0, 0, 0)>(vb), h0 = tr_read<v_rd_off(D0, 0, 1)>(vb), l1 = tr_read<v_rd_off(D0, 1, 0)>(vb), h1 = tr_read<v_rd_off(D0, 1, 1)>(vb);
;   const s16x4 l2 = tr_read<v_rd_off(D0, 2, 0)>(vb), h2 = tr_read<v_rd_off(D0, 2, 1)>(vb), l3 = tr_read<v_rd_off(D0, 3, 0)>(vb), h3 = tr_read<v_rd_off(D0, 3, 1)>(vb);
;   asm volatile("s_waitcnt lgkmcnt(0)" ::: "memory"); SBAR();
;     ...
;   od = __builtin_amdgcn_mfma_f32_32x32x16_bf16(pa0, PK(l0, h0), od, 0, 0, 0);
;   od = __builtin_amdgcn_mfma_f32_32x32x16_bf16(pa1, PK(l1, h1), od, 0, 0, 0);
.LBB0_76:
	ds_read_b128 v[64:67], v193 offset:49152
	ds_read_b128 v[68:71], v193 offset:57344
	ds_read_b128 v[222:225], v198 offset:49152
	ds_read_b128 v[226:229], v198 offset:57344
	v_add_f32_e32 v160, 0, v161
	v_add_f32_e32 v160, v175, v160
	s_waitcnt lgkmcnt(3)
	v_mfma_f32_32x32x16_bf16 v[80:95], v[64:67], v[112:115], 0
	v_add_f32_e32 v160, v162, v160
	v_add_f32_e32 v160, v205, v160
	v_add_f32_e32 v160, v174, v160
	v_add_f32_e32 v160, v214, v160
	v_add_f32_e32 v160, v163, v160
	v_add_f32_e32 v160, v173, v160
	v_add_f32_e32 v160, v164, v160
	s_waitcnt lgkmcnt(2)
	v_mfma_f32_32x32x16_bf16 v[64:79], v[68:71], v[112:115], 0
	v_add_f32_e32 v160, v171, v160
	v_add_f32_e32 v160, v165, v160
	v_add_f32_e32 v160, v172, v160
	v_exp_f32_e32 v158, v158
	v_add_f32_e32 v160, v166, v160
	v_exp_f32_e32 v159, v159
	v_add_f32_e32 v160, v169, v160
	s_waitcnt lgkmcnt(1)
	v_mfma_f32_32x32x16_bf16 v[80:95], v[222:225], v[108:111], v[80:95]
	v_exp_f32_e32 v156, v156
	v_add_f32_e32 v160, v167, v160
	v_exp_f32_e32 v157, v157
	v_add_f32_e32 v160, v170, v160
	v_exp_f32_e32 v152, v152
	v_add_f32_e32 v160, v158, v160
	v_exp_f32_e32 v153, v153
	s_waitcnt lgkmcnt(0)
	v_mfma_f32_32x32x16_bf16 v[64:79], v[226:229], v[108:111], v[64:79]
	ds_read_b128 v[222:225], v197 offset:49152
	ds_read_b128 v[226:229], v197 offset:57344
	v_add_f32_e32 v160, v159, v160
	v_exp_f32_e32 v148, v148
	v_add_f32_e32 v160, v156, v160
	v_exp_f32_e32 v149, v149
	v_add_f32_e32 v160, v157, v160
	v_exp_f32_e32 v146, v146
	s_waitcnt lgkmcnt(1)
	v_mfma_f32_32x32x16_bf16 v[80:95], v[222:225], v[120:123], v[80:95]
	v_add_f32_e32 v160, v152, v160
	v_exp_f32_e32 v147, v147
	v_add_f32_e32 v160, v153, v160
	v_exp_f32_e32 v154, v154
	v_add_f32_e32 v160, v148, v160
	v_exp_f32_e32 v155, v155
	v_add_f32_e32 v160, v149, v160
	s_waitcnt lgkmcnt(0)
	v_mfma_f32_32x32x16_bf16 v[64:79], v[226:229], v[120:123], v[64:79]
	ds_read_b128 v[222:225], v196 offset:49152
	ds_read_b128 v[226:229], v196 offset:57344
	v_exp_f32_e32 v150, v150
	v_add_f32_e32 v160, v146, v160
	v_exp_f32_e32 v151, v151
	v_add_f32_e32 v160, v147, v160
	v_exp_f32_e32 v144, v144
	v_add_f32_e32 v160, v154, v160
	s_waitcnt lgkmcnt(1)
	v_mfma_f32_32x32x16_bf16 v[80:95], v[222:225], v[124:127], v[80:95]
	v_exp_f32_e32 v145, v145
	v_add_f32_e32 v160, v155, v160
	v_add_f32_e32 v160, v150, v160
	v_add_f32_e32 v160, v151, v160
	v_add_f32_e32 v160, v144, v160
	v_add_f32_e32 v202, v145, v160
	v_mov_b32_e32 v203, v202
	s_waitcnt lgkmcnt(0)
	v_mfma_f32_32x32x16_bf16 v[64:79], v[226:229], v[124:127], v[64:79]
	ds_read_b128 v[222:225], v194 offset:49152
	ds_read_b128 v[226:229], v194 offset:57344
	v_permlane32_swap_b32_e32 v202, v203
	s_waitcnt lgkmcnt(1)
	v_mfma_f32_32x32x16_bf16 v[80:95], v[222:225], v[116:119], v[80:95]
	s_waitcnt lgkmcnt(0)
	v_mfma_f32_32x32x16_bf16 v[64:79], v[226:229], v[116:119], v[64:79]
	ds_read_b128 v[222:225], v195 offset:49152
	ds_read_b128 v[226:229], v195 offset:57344
	s_waitcnt lgkmcnt(1)
	v_mfma_f32_32x32x16_bf16 v[80:95], v[222:225], v[104:107], v[80:95]
	s_waitcnt lgkmcnt(0)
	v_mfma_f32_32x32x16_bf16 v[64:79], v[226:229], v[104:107], v[64:79]
	ds_read_b128 v[222:225], v200 offset:49152
	ds_read_b128 v[226:229], v200 offset:57344
	s_waitcnt lgkmcnt(1)
	v_mfma_f32_32x32x16_bf16 v[80:95], v[222:225], v[100:103], v[80:95]
	s_waitcnt lgkmcnt(0)
	v_mfma_f32_32x32x16_bf16 v[64:79], v[226:229], v[100:103], v[64:79]
	ds_read_b128 v[222:225], v199 offset:49152
	ds_read_b128 v[226:229], v199 offset:57344
	v_cvt_pk_bf16_f32 v160, v161, v175
	v_cvt_pk_bf16_f32 v161, v162, v205
	v_cvt_pk_bf16_f32 v162, v174, v214
	v_cvt_pk_bf16_f32 v163, v163, v173
	v_cvt_pk_bf16_f32 v164, v164, v171
	v_cvt_pk_bf16_f32 v165, v165, v172
	s_waitcnt lgkmcnt(1)
	v_mfma_f32_32x32x16_bf16 v[80:95], v[222:225], v[96:99], v[80:95]
	v_cvt_pk_bf16_f32 v166, v166, v169
	v_cvt_pk_bf16_f32 v167, v167, v170
	v_cvt_pk_bf16_f32 v170, v158, v159
	v_cvt_pk_bf16_f32 v171, v156, v157
	v_cvt_pk_bf16_f32 v172, v152, v153
	v_cvt_pk_bf16_f32 v173, v148, v149
	v_cvt_pk_bf16_f32 v204, v146, v147
	s_waitcnt lgkmcnt(0)
	v_mfma_f32_32x32x16_bf16 v[64:79], v[226:229], v[96:99], v[64:79]
	v_cvt_pk_bf16_f32 v205, v154, v155
	v_cvt_pk_bf16_f32 v206, v150, v151
	v_permlane32_swap_b32_e32 v160, v162
	v_cvt_pk_bf16_f32 v207, v144, v145
	v_permlane32_swap_b32_e32 v204, v206
	v_permlane32_swap_b32_e32 v161, v163
	v_permlane32_swap_b32_e32 v164, v166
	v_permlane32_swap_b32_e32 v165, v167
	v_permlane32_swap_b32_e32 v170, v172
	v_permlane32_swap_b32_e32 v171, v173
	v_permlane32_swap_b32_e32 v205, v207
	ds_read_b64_tr_b16 v[222:223], v188 offset:0
	ds_read_b64_tr_b16 v[224:225], v188 offset:0x800
	ds_read_b64_tr_b16 v[226:227], v188 offset:0x1000
	ds_read_b64_tr_b16 v[228:229], v188 offset:0x1800
	ds_read_b64_tr_b16 v[230:231], v188 offset:0x2000
	ds_read_b64_tr_b16 v[232:233], v188 offset:0x2800
	ds_read_b64_tr_b16 v[234:235], v188 offset:0x3000
	ds_read_b64_tr_b16 v[236:237], v188 offset:0x3800
	s_waitcnt lgkmcnt(0)
	s_nop 0
	v_mfma_f32_32x32x16_bf16 v[0:15], v[160:163], v[222:225], v[0:15]
	ds_read_b64_tr_b16 v[222:223], v188 offset:0x200
	ds_read_b64_tr_b16 v[224:225], v188 offset:0xa00
	v_mfma_f32_32x32x16_bf16 v[0:15], v[164:167], v[226:229], v[0:15]
	ds_read_b64_tr_b16 v[226:227], v188 offset:0x1200
	ds_read_b64_tr_b16 v[228:229], v188 offset:0x1a00
	v_mfma_f32_32x32x16_bf16 v[0:15], v[170:173], v[230:233], v[0:15]
	ds_read_b64_tr_b16 v[230:231], v188 offset:0x2200
	ds_read_b64_tr_b16 v[232:233], v188 offset:0x2a00
	v_mfma_f32_32x32x16_bf16 v[0:15], v[204:207], v[234:237], v[0:15]
	ds_read_b64_tr_b16 v[234:235], v188 offset:0x3200
	ds_read_b64_tr_b16 v[236:237], v188 offset:0x3a00
	s_waitcnt lgkmcnt(0)
; #define SBAR() __builtin_amdgcn_sched_barrier(0)
; __device__ __forceinline__ void partialSM(f32x16& p0, f32x16& p1, float& m_reg, float& mn, float& alpha) {
;   constexpr float C = SCALE * 1.4426950408889634f;
;   float pmax = p0[0]; for (int r = 1; r < 16; ++r) pmax = fmaxf(pmax, p0[r]); for (int r = 0; r < 16; ++r) pmax = fmaxf(pmax, p1[r]);
;   { auto rr = __builtin_amdgcn_permlane32_swap(__float_as_uint(pmax), __float_as_uint(pmax), false, false);
;     pmax = fmaxf(__uint_as_float(rr[0]), __uint_as_float(rr[1])); }
;   if (__builtin_expect(__all(pmax - m_reg <= THR / SCALE), 1)) { mn = m_reg; alpha = 1.f; }
;   else { mn = fmaxf(m_reg, pmax); alpha = __builtin_amdgcn_exp2f((m_reg - mn) * C); m_reg = mn; }
; template <int D0> __device__ __forceinline__ void pv_one(f32x16& od, int vb, bf16x8 pa0, bf16x8 pa1, bf16x8 pa2, bf16x8 pa3) {
;   const s16x4 l0 = tr_read<v_rd_off(D0, 0, 0)>(vb), h0 = tr_read<v_rd_off(D0, 0, 1)>(vb), l1 = tr_read<v_rd_off(D0, 1, 0)>(vb), h1 = tr_read<v_rd_off(D0, 1, 1)>(vb);
;   const s16x4 l2 = tr_read<v_rd_off(D0, 2, 0)>(vb), h2 = tr_read<v_rd_off(D0, 2, 1)>(vb), l3 = tr_read<v_rd_off(D0, 3, 0)>(vb), h3 = tr_read<v_rd_off(D0, 3, 1)>(vb);
;   asm volatile("s_waitcnt lgkmcnt(0)" ::: "memory"); SBAR();
;     ...
;   od = __builtin_amdgcn_mfma_f32_32x32x16_bf16(pa0, PK(l0, h0), od, 0, 0, 0);
;   od = __builtin_amdgcn_mfma_f32_32x32x16_bf16(pa1, PK(l1, h1), od, 0, 0, 0);
;   od = __builtin_amdgcn_mfma_f32_32x32x16_bf16(pa2, PK(l2, h2), od, 0, 0, 0);
;   od = __builtin_amdgcn_mfma_f32_32x32x16_bf16(pa3, PK(l3, h3), od, 0, 0, 0);
	v_mfma_f32_32x32x16_bf16 v[48:63], v[160:163], v[222:225], v[48:63]
	ds_read_b64_tr_b16 v[222:223], v188 offset:0x400
	ds_read_b64_tr_b16 v[224:225], v188 offset:0xc00
	v_mfma_f32_32x32x16_bf16 v[48:63], v[164:167], v[226:229], v[48:63]
	ds_read_b64_tr_b16 v[226:227], v188 offset:0x1400
	ds_read_b64_tr_b16 v[228:229], v188 offset:0x1c00
	v_mfma_f32_32x32x16_bf16 v[48:63], v[170:173], v[230:233], v[48:63]
	ds_read_b64_tr_b16 v[230:231], v188 offset:0x2400
	ds_read_b64_tr_b16 v[232:233], v188 offset:0x2c00
	v_mfma_f32_32x32x16_bf16 v[48:63], v[204:207], v[234:237], v[48:63]
	ds_read_b64_tr_b16 v[234:235], v188 offset:0x3400
	ds_read_b64_tr_b16 v[236:237], v188 offset:0x3c00
	s_waitcnt lgkmcnt(0)
	v_mfma_f32_32x32x16_bf16 v[32:47], v[160:163], v[222:225], v[32:47]
	ds_read_b64_tr_b16 v[222:223], v188 offset:0x600
	ds_read_b64_tr_b16 v[224:225], v188 offset:0xe00
	v_mfma_f32_32x32x16_bf16 v[32:47], v[164:167], v[226:229], v[32:47]
	ds_read_b64_tr_b16 v[226:227], v188 offset:0x1600
	ds_read_b64_tr_b16 v[228:229], v188 offset:0x1e00
	v_mfma_f32_32x32x16_bf16 v[32:47], v[170:173], v[230:233], v[32:47]
	ds_read_b64_tr_b16 v[230:231], v188 offset:0x2600
	ds_read_b64_tr_b16 v[232:233], v188 offset:0x2e00
	v_mfma_f32_32x32x16_bf16 v[32:47], v[204:207], v[234:237], v[32:47]
	ds_read_b64_tr_b16 v[234:235], v188 offset:0x3600
	ds_read_b64_tr_b16 v[236:237], v188 offset:0x3e00
	s_waitcnt lgkmcnt(0)
	v_mfma_f32_32x32x16_bf16 v[16:31], v[160:163], v[222:225], v[16:31]
	v_max_f32_e32 v160, v81, v81
	v_max_f32_e32 v161, v80, v80
	v_max_f32_e32 v160, v161, v160
	v_max3_f32 v160, v160, v82, v83
	v_max3_f32 v160, v160, v84, v85
	v_max3_f32 v160, v160, v86, v87
	v_max3_f32 v160, v160, v88, v89
	v_max3_f32 v160, v160, v90, v91
	v_max3_f32 v160, v160, v92, v93
	v_mfma_f32_32x32x16_bf16 v[16:31], v[164:167], v[226:229], v[16:31]
	v_max3_f32 v160, v160, v94, v95
	v_max3_f32 v160, v160, v64, v65
	v_max3_f32 v160, v160, v66, v67
	v_max3_f32 v160, v160, v68, v69
	v_max3_f32 v160, v160, v70, v71
	v_max3_f32 v160, v160, v72, v73
	v_max3_f32 v160, v160, v74, v75
	v_max3_f32 v160, v160, v76, v77
	v_mfma_f32_32x32x16_bf16 v[16:31], v[170:173], v[230:233], v[16:31]
	v_max3_f32 v160, v160, v78, v79
	v_mov_b32_e32 v161, v160
	s_nop 1
	v_permlane32_swap_b32_e32 v160, v161
	v_max_f32_e32 v161, v161, v161
	v_max_f32_e32 v160, v160, v160
	v_max_f32_e32 v160, v160, v161
	v_sub_f32_e32 v161, v160, v168
	v_cmp_ge_f32_e32 vcc, s4, v161
	v_max_f32_e32 v161, v168, v168
	v_max_f32_e32 v160, v161, v160
	v_mfma_f32_32x32x16_bf16 v[16:31], v[204:207], v[234:237], v[16:31]
	v_sub_f32_e32 v161, v168, v160
	v_mul_f32_e32 v161, 0x3e0293ee, v161
	v_exp_f32_e32 v161, v161
	s_cmp_eq_u64 vcc, exec
	s_cselect_b64 s[0:1], -1, 0
	s_cmp_ge_u32 s5, 0x2000
	s_cbranch_scc1 .Latt_nb_p0a
	s_waitcnt vmcnt(4)
	s_barrier
.Latt_nb_p0a:
	v_cndmask_b32_e64 v204, v161, 1.0, s[0:1]
	v_cmp_gt_f32_e32 vcc, 1.0, v204
	s_add_i32 m0, s5, s28
	s_add_i32 m0, m0, 0x8000
	s_nop 0
	global_load_lds_dwordx4 v128, s[6:7]
	s_add_i32 m0, s5, s28
	s_add_i32 m0, m0, 0x8400
	s_nop 0
	global_load_lds_dwordx4 v129, s[6:7]
	s_add_i32 m0, s5, s29
	s_add_i32 m0, m0, 0x4000
	s_nop 0
	global_load_lds_dwordx4 v130, s[68:69]
	s_add_i32 m0, s5, s29
	s_add_i32 m0, m0, 0x4400
	s_nop 0
	global_load_lds_dwordx4 v131, s[68:69]
	s_add_u32 s6, s6, 0x4000
	s_addc_u32 s7, s7, 0
	s_add_u32 s68, s68, 0x4000
	s_addc_u32 s69, s69, 0
	v_xor_b32_e32 v193, 0x10000, v193
	v_xor_b32_e32 v194, 0x10000, v194
	v_xor_b32_e32 v195, 0x10000, v195
	v_xor_b32_e32 v196, 0x10000, v196
	v_xor_b32_e32 v197, 0x10000, v197
	v_xor_b32_e32 v198, 0x10000, v198
	v_xor_b32_e32 v199, 0x10000, v199
	v_xor_b32_e32 v200, 0x10000, v200
	s_cbranch_vccz .LBB0_80
	s_and_saveexec_b64 s[42:43], s[38:39]
	ds_write_b32 v185, v204 offset:128
	s_or_b64 exec, exec, s[42:43]
	s_waitcnt lgkmcnt(0)
	v_add_u32_e32 v161, v184, v208
	ds_read_b128 v[162:165], v161 offset:224
	ds_read_b128 v[170:173], v161 offset:192
	ds_read_b128 v[222:225], v161 offset:160
	ds_read_b128 v[226:229], v161 offset:128
	s_waitcnt lgkmcnt(3)
	v_pk_mul_f32 v[12:13], v[12:13], v[162:163]
	s_waitcnt lgkmcnt(2)
	v_pk_mul_f32 v[8:9], v[8:9], v[170:171]
	s_waitcnt lgkmcnt(1)
	v_pk_mul_f32 v[4:5], v[4:5], v[222:223]
	v_pk_mul_f32 v[14:15], v[14:15], v[164:165]
	v_pk_mul_f32 v[10:11], v[10:11], v[172:173]
	v_pk_mul_f32 v[6:7], v[6:7], v[224:225]
	s_waitcnt lgkmcnt(0)
	v_pk_mul_f32 v[2:3], v[2:3], v[228:229]
	v_pk_mul_f32 v[0:1], v[0:1], v[226:227]
	v_pk_mul_f32 v[60:61], v[60:61], v[162:163]
	v_pk_mul_f32 v[56:57], v[56:57], v[170:171]
	v_pk_mul_f32 v[52:53], v[52:53], v[222:223]
	v_pk_mul_f32 v[62:63], v[62:63], v[164:165]
	v_pk_mul_f32 v[58:59], v[58:59], v[172:173]
	v_pk_mul_f32 v[54:55], v[54:55], v[224:225]
	v_pk_mul_f32 v[50:51], v[50:51], v[228:229]
	v_pk_mul_f32 v[48:49], v[48:49], v[226:227]
	v_pk_mul_f32 v[44:45], v[44:45], v[162:163]
	v_pk_mul_f32 v[40:41], v[40:41], v[170:171]
	v_pk_mul_f32 v[36:37], v[36:37], v[222:223]
	v_pk_mul_f32 v[46:47], v[46:47], v[164:165]
	v_pk_mul_f32 v[42:43], v[42:43], v[172:173]
	v_pk_mul_f32 v[38:39], v[38:39], v[224:225]
	v_pk_mul_f32 v[34:35], v[34:35], v[228:229]
	v_pk_mul_f32 v[32:33], v[32:33], v[226:227]
	v_pk_mul_f32 v[28:29], v[28:29], v[162:163]
	v_pk_mul_f32 v[24:25], v[24:25], v[170:171]
	v_pk_mul_f32 v[20:21], v[20:21], v[222:223]
	v_pk_mul_f32 v[30:31], v[30:31], v[164:165]
	v_pk_mul_f32 v[26:27], v[26:27], v[172:173]
	v_pk_mul_f32 v[22:23], v[22:23], v[224:225]
	v_pk_mul_f32 v[18:19], v[18:19], v[228:229]
	v_pk_mul_f32 v[16:17], v[16:17], v[226:227]
; __device__ __forceinline__ void partialSM(f32x16& p0, f32x16& p1, float& m_reg, float& mn, float& alpha) {
;     ...
;   float mnC = -mn * C;
;   for (int r = 0; r < 16; ++r) p0[r] = fmaf(p0[r], C, mnC); for (int r = 0; r < 16; ++r) p1[r] = fmaf(p1[r], C, mnC);
;   for (int r = 0; r < 16; ++r) p0[r] = __builtin_amdgcn_exp2f(p0[r]);
; }
; __device__ __forceinline__ void finishSM(f32x16& p0, f32x16& p1, float alpha, float& l_reg, bf16x8& pa0, bf16x8& pa1, bf16x8& pa2, bf16x8& pa3) {
;   for (int r = 0; r < 16; ++r) p1[r] = __builtin_amdgcn_exp2f(p1[r]);
;   float ps = 0; for (int r = 0; r < 16; ++r) ps += p0[r]; for (int r = 0; r < 16; ++r) ps += p1[r];
;   { auto rr = __builtin_amdgcn_permlane32_swap(__float_as_uint(ps), __float_as_uint(ps), false, false);
;     ps = __uint_as_float(rr[0]) + __uint_as_float(rr[1]); }
;   l_reg = l_reg * alpha + ps;
;     ...
;   PK4(p0, 0, pa0); PK4(p0, 8, pa1); PK4(p1, 0, pa2); PK4(p1, 8, pa3);
;     ...
; }
; __device__ __forceinline__ void qkt(f32x16& p0, f32x16& p1, const bf16* Ks, const bf16x8* qr, int r32, int hi) {
;   p0 = f32x16{}; p1 = f32x16{};
;   for (int d0 = 0; d0 < 8; ++d0) { int cb = (d0 * 16 + hi * 8) * 2;
;     bf16x8 b0 = *reinterpret_cast<const bf16x8*>((const char*)Ks + KSWZ(r32, cb));
;     bf16x8 b1 = *reinterpret_cast<const bf16x8*>((const char*)Ks + KSWZ(32 + r32, cb));
;     p0 = __builtin_amdgcn_mfma_f32_32x32x16_bf16(b0, qr[d0], p0, 0, 0, 0);
;     p1 = __builtin_amdgcn_mfma_f32_32x32x16_bf16(b1, qr[d0], p1, 0, 0, 0); }
.LBB0_80:
	v_cndmask_b32_e64 v205, v160, v168, s[0:1]
	v_mul_f32_e32 v206, 0xbe0293ee, v205
	v_fmamk_f32 v80, v80, 0x3e0293ee, v206
	v_fmamk_f32 v81, v81, 0x3e0293ee, v206
	v_fmamk_f32 v82, v82, 0x3e0293ee, v206
	v_fmamk_f32 v83, v83, 0x3e0293ee, v206
	v_fmamk_f32 v84, v84, 0x3e0293ee, v206
	v_fmamk_f32 v85, v85, 0x3e0293ee, v206
	v_fmamk_f32 v86, v86, 0x3e0293ee, v206
	v_fmamk_f32 v87, v87, 0x3e0293ee, v206
	v_fmamk_f32 v88, v88, 0x3e0293ee, v206
	v_fmamk_f32 v89, v89, 0x3e0293ee, v206
	v_fmamk_f32 v90, v90, 0x3e0293ee, v206
	v_fmamk_f32 v91, v91, 0x3e0293ee, v206
	v_fmamk_f32 v92, v92, 0x3e0293ee, v206
	v_fmamk_f32 v93, v93, 0x3e0293ee, v206
	v_fmamk_f32 v94, v94, 0x3e0293ee, v206
	v_fmamk_f32 v95, v95, 0x3e0293ee, v206
	v_exp_f32_e32 v160, v80
	v_exp_f32_e32 v175, v81
	v_exp_f32_e32 v161, v82
	v_exp_f32_e32 v174, v83
	v_exp_f32_e32 v162, v84
	v_exp_f32_e32 v173, v85
	v_exp_f32_e32 v163, v86
	v_exp_f32_e32 v172, v87
	v_exp_f32_e32 v164, v88
	v_exp_f32_e32 v171, v89
	v_exp_f32_e32 v165, v90
	v_exp_f32_e32 v170, v91
	v_exp_f32_e32 v166, v92
	v_exp_f32_e32 v169, v93
	v_exp_f32_e32 v167, v94
	v_exp_f32_e32 v168, v95
	v_fmamk_f32 v227, v64, 0x3e0293ee, v206
	v_fmamk_f32 v228, v65, 0x3e0293ee, v206
	v_fmamk_f32 v229, v66, 0x3e0293ee, v206
	v_fmamk_f32 v230, v67, 0x3e0293ee, v206
	v_fmamk_f32 v231, v68, 0x3e0293ee, v206
	v_fmamk_f32 v214, v69, 0x3e0293ee, v206
	v_fmamk_f32 v215, v70, 0x3e0293ee, v206
	v_fmamk_f32 v222, v71, 0x3e0293ee, v206
	v_fmamk_f32 v223, v72, 0x3e0293ee, v206
	v_fmamk_f32 v224, v73, 0x3e0293ee, v206
	v_fmamk_f32 v225, v74, 0x3e0293ee, v206
	v_fmamk_f32 v226, v75, 0x3e0293ee, v206
	v_fmamk_f32 v207, v76, 0x3e0293ee, v206
	v_fmamk_f32 v232, v77, 0x3e0293ee, v206
	v_fmamk_f32 v233, v78, 0x3e0293ee, v206
	v_fmac_f32_e32 v206, 0x3e0293ee, v79
	s_waitcnt lgkmcnt(0)
	s_cmp_ge_u32 s5, 0x2000
	s_cbranch_scc0 .Latt_nb_p1a
	s_waitcnt vmcnt(4)
	s_barrier
.Latt_nb_p1a:
	ds_read_b128 v[64:67], v193 offset:32768
	ds_read_b128 v[68:71], v193 offset:40960
	ds_read_b128 v[234:237], v198 offset:32768
	ds_read_b128 v[238:241], v198 offset:40960
	v_exp_f32_e32 v216, v227
	v_exp_f32_e32 v227, v229
	s_waitcnt lgkmcnt(3)
	v_mfma_f32_32x32x16_bf16 v[80:95], v[64:67], v[112:115], 0
	v_exp_f32_e32 v229, v231
	v_exp_f32_e32 v231, v232
	v_exp_f32_e32 v232, v233
	v_exp_f32_e32 v233, v206
	v_add_f32_e32 v206, 0, v160
	v_add_f32_e32 v206, v175, v206
	v_add_f32_e32 v206, v161, v206
	s_waitcnt lgkmcnt(2)
	v_mfma_f32_32x32x16_bf16 v[64:79], v[68:71], v[112:115], 0
	v_add_f32_e32 v206, v174, v206
	v_add_f32_e32 v206, v162, v206
	v_add_f32_e32 v206, v173, v206
	v_add_f32_e32 v206, v163, v206
	v_add_f32_e32 v206, v172, v206
	v_add_f32_e32 v206, v164, v206
	v_add_f32_e32 v206, v171, v206
	s_waitcnt lgkmcnt(1)
	v_mfma_f32_32x32x16_bf16 v[80:95], v[234:237], v[108:111], v[80:95]
	v_add_f32_e32 v206, v165, v206
	v_add_f32_e32 v206, v170, v206
	v_add_f32_e32 v206, v166, v206
	v_exp_f32_e32 v217, v228
	v_add_f32_e32 v206, v169, v206
	v_add_f32_e32 v206, v167, v206
	v_exp_f32_e32 v228, v230
	s_waitcnt lgkmcnt(0)
	v_mfma_f32_32x32x16_bf16 v[64:79], v[238:241], v[108:111], v[64:79]
	ds_read_b128 v[234:237], v197 offset:32768
	ds_read_b128 v[238:241], v197 offset:40960
	v_add_f32_e32 v206, v168, v206
	v_add_f32_e32 v206, v216, v206
	v_exp_f32_e32 v214, v214
	v_add_f32_e32 v206, v217, v206
	v_exp_f32_e32 v215, v215
	v_add_f32_e32 v206, v227, v206
	s_waitcnt lgkmcnt(1)
	v_mfma_f32_32x32x16_bf16 v[80:95], v[234:237], v[120:123], v[80:95]
	v_exp_f32_e32 v222, v222
	v_add_f32_e32 v206, v228, v206
	v_exp_f32_e32 v223, v223
	v_add_f32_e32 v206, v229, v206
	v_exp_f32_e32 v224, v224
	v_add_f32_e32 v206, v214, v206
	v_exp_f32_e32 v225, v225
	s_waitcnt lgkmcnt(0)
	v_mfma_f32_32x32x16_bf16 v[64:79], v[238:241], v[120:123], v[64:79]
	ds_read_b128 v[234:237], v196 offset:32768
	ds_read_b128 v[238:241], v196 offset:40960
	v_add_f32_e32 v206, v215, v206
	v_exp_f32_e32 v226, v226
	v_add_f32_e32 v206, v222, v206
	v_exp_f32_e32 v230, v207
	v_add_f32_e32 v206, v223, v206
	v_add_f32_e32 v206, v224, v206
	s_waitcnt lgkmcnt(1)
	v_mfma_f32_32x32x16_bf16 v[80:95], v[234:237], v[124:127], v[80:95]
	v_add_f32_e32 v206, v225, v206
	v_add_f32_e32 v206, v226, v206
	v_add_f32_e32 v206, v230, v206
	v_add_f32_e32 v206, v231, v206
	v_add_f32_e32 v206, v232, v206
	v_add_f32_e32 v206, v233, v206
	v_mov_b32_e32 v207, v206
	s_waitcnt lgkmcnt(0)
	v_mfma_f32_32x32x16_bf16 v[64:79], v[238:241], v[124:127], v[64:79]
	ds_read_b128 v[234:237], v194 offset:32768
	ds_read_b128 v[238:241], v194 offset:40960
	v_permlane32_swap_b32_e32 v206, v207
	s_waitcnt lgkmcnt(1)
	v_mfma_f32_32x32x16_bf16 v[80:95], v[234:237], v[116:119], v[80:95]
	s_waitcnt lgkmcnt(0)
	v_mfma_f32_32x32x16_bf16 v[64:79], v[238:241], v[116:119], v[64:79]
	ds_read_b128 v[234:237], v195 offset:32768
	ds_read_b128 v[238:241], v195 offset:40960
	s_waitcnt lgkmcnt(1)
	v_mfma_f32_32x32x16_bf16 v[80:95], v[234:237], v[104:107], v[80:95]
	s_waitcnt lgkmcnt(0)
	v_mfma_f32_32x32x16_bf16 v[64:79], v[238:241], v[104:107], v[64:79]
	ds_read_b128 v[234:237], v200 offset:32768
	ds_read_b128 v[238:241], v200 offset:40960
	s_waitcnt lgkmcnt(1)
	v_mfma_f32_32x32x16_bf16 v[80:95], v[234:237], v[100:103], v[80:95]
	s_waitcnt lgkmcnt(0)
	v_mfma_f32_32x32x16_bf16 v[64:79], v[238:241], v[100:103], v[64:79]
	ds_read_b128 v[234:237], v199 offset:32768
	ds_read_b128 v[238:241], v199 offset:40960
	v_cvt_pk_bf16_f32 v160, v160, v175
	v_cvt_pk_bf16_f32 v161, v161, v174
	v_cvt_pk_bf16_f32 v162, v162, v173
	v_cvt_pk_bf16_f32 v163, v163, v172
	v_cvt_pk_bf16_f32 v164, v164, v171
	v_cvt_pk_bf16_f32 v165, v165, v170
	s_waitcnt lgkmcnt(1)
	v_mfma_f32_32x32x16_bf16 v[80:95], v[234:237], v[96:99], v[80:95]
	v_cvt_pk_bf16_f32 v166, v166, v169
	v_cvt_pk_bf16_f32 v167, v167, v168
	v_cvt_pk_bf16_f32 v168, v216, v217
	v_cvt_pk_bf16_f32 v169, v227, v228
	v_cvt_pk_bf16_f32 v170, v229, v214
	v_cvt_pk_bf16_f32 v171, v215, v222
	v_cvt_pk_bf16_f32 v172, v223, v224
	s_waitcnt lgkmcnt(0)
	v_mfma_f32_32x32x16_bf16 v[64:79], v[238:241], v[96:99], v[64:79]
	v_cvt_pk_bf16_f32 v173, v225, v226
	v_cvt_pk_bf16_f32 v174, v230, v231
	v_cvt_pk_bf16_f32 v175, v232, v233
	v_permlane32_swap_b32_e32 v160, v162
	v_permlane32_swap_b32_e32 v161, v163
	v_permlane32_swap_b32_e32 v164, v166
	v_permlane32_swap_b32_e32 v165, v167
	v_permlane32_swap_b32_e32 v168, v170
	v_permlane32_swap_b32_e32 v169, v171
	v_permlane32_swap_b32_e32 v172, v174
	v_permlane32_swap_b32_e32 v173, v175
	s_cmp_ge_u32 s2, s27
	s_cselect_b64 s[42:43], -1, 0
	s_and_b64 vcc, exec, s[42:43]
	s_cbranch_vccnz .LBB0_82
; #define SBAR() __builtin_amdgcn_sched_barrier(0)
; __device__ __forceinline__ void partialSM(f32x16& p0, f32x16& p1, float& m_reg, float& mn, float& alpha) {
;   constexpr float C = SCALE * 1.4426950408889634f;
;   float pmax = p0[0]; for (int r = 1; r < 16; ++r) pmax = fmaxf(pmax, p0[r]); for (int r = 0; r < 16; ++r) pmax = fmaxf(pmax, p1[r]);
;   { auto rr = __builtin_amdgcn_permlane32_swap(__float_as_uint(pmax), __float_as_uint(pmax), false, false);
;     pmax = fmaxf(__uint_as_float(rr[0]), __uint_as_float(rr[1])); }
;   if (__builtin_expect(__all(pmax - m_reg <= THR / SCALE), 1)) { mn = m_reg; alpha = 1.f; }
;   else { mn = fmaxf(m_reg, pmax); alpha = __builtin_amdgcn_exp2f((m_reg - mn) * C); m_reg = mn; }
; template <int D0> __device__ __forceinline__ void pv_one(f32x16& od, int vb, bf16x8 pa0, bf16x8 pa1, bf16x8 pa2, bf16x8 pa3) {
;   const s16x4 l0 = tr_read<v_rd_off(D0, 0, 0)>(vb), h0 = tr_read<v_rd_off(D0, 0, 1)>(vb), l1 = tr_read<v_rd_off(D0, 1, 0)>(vb), h1 = tr_read<v_rd_off(D0, 1, 1)>(vb);
;   const s16x4 l2 = tr_read<v_rd_off(D0, 2, 0)>(vb), h2 = tr_read<v_rd_off(D0, 2, 1)>(vb), l3 = tr_read<v_rd_off(D0, 3, 0)>(vb), h3 = tr_read<v_rd_off(D0, 3, 1)>(vb);
;   asm volatile("s_waitcnt lgkmcnt(0)" ::: "memory"); SBAR();
;     ...
;   od = __builtin_amdgcn_mfma_f32_32x32x16_bf16(pa0, PK(l0, h0), od, 0, 0, 0);
;   od = __builtin_amdgcn_mfma_f32_32x32x16_bf16(pa1, PK(l1, h1), od, 0, 0, 0);
;   od = __builtin_amdgcn_mfma_f32_32x32x16_bf16(pa2, PK(l2, h2), od, 0, 0, 0);
;   od = __builtin_amdgcn_mfma_f32_32x32x16_bf16(pa3, PK(l3, h3), od, 0, 0, 0);
;     ...
; }
; __device__ __forceinline__ void pv_d0(f32x16* o, int vb, bf16x8 pa0, bf16x8 pa1, bf16x8 pa2, bf16x8 pa3) {
;   pv_one<0>(o[0], vb, pa0, pa1, pa2, pa3); pv_one<1>(o[1], vb, pa0, pa1, pa2, pa3); pv_one<2>(o[2], vb, pa0, pa1, pa2, pa3); pv_one<3>(o[3], vb, pa0, pa1, pa2, pa3);
.LBB0_82:
	ds_read_b64_tr_b16 v[222:223], v187 offset:0
	ds_read_b64_tr_b16 v[224:225], v187 offset:0x800
	ds_read_b64_tr_b16 v[226:227], v187 offset:0x1000
	ds_read_b64_tr_b16 v[228:229], v187 offset:0x1800
	ds_read_b64_tr_b16 v[230:231], v187 offset:0x2000
	ds_read_b64_tr_b16 v[232:233], v187 offset:0x2800
	ds_read_b64_tr_b16 v[234:235], v187 offset:0x3000
	ds_read_b64_tr_b16 v[236:237], v187 offset:0x3800
	s_waitcnt lgkmcnt(0)
	s_nop 0
	v_mfma_f32_32x32x16_bf16 v[0:15], v[160:163], v[222:225], v[0:15]
	ds_read_b64_tr_b16 v[222:223], v187 offset:0x200
	ds_read_b64_tr_b16 v[224:225], v187 offset:0xa00
	v_mfma_f32_32x32x16_bf16 v[0:15], v[164:167], v[226:229], v[0:15]
	ds_read_b64_tr_b16 v[226:227], v187 offset:0x1200
	ds_read_b64_tr_b16 v[228:229], v187 offset:0x1a00
	v_mfma_f32_32x32x16_bf16 v[0:15], v[168:171], v[230:233], v[0:15]
	ds_read_b64_tr_b16 v[230:231], v187 offset:0x2200
	ds_read_b64_tr_b16 v[232:233], v187 offset:0x2a00
	v_mfma_f32_32x32x16_bf16 v[0:15], v[172:175], v[234:237], v[0:15]
	ds_read_b64_tr_b16 v[234:235], v187 offset:0x3200
	ds_read_b64_tr_b16 v[236:237], v187 offset:0x3a00
	s_waitcnt lgkmcnt(0)
	v_mfma_f32_32x32x16_bf16 v[48:63], v[160:163], v[222:225], v[48:63]
	ds_read_b64_tr_b16 v[222:223], v187 offset:0x400
	ds_read_b64_tr_b16 v[224:225], v187 offset:0xc00
	v_mfma_f32_32x32x16_bf16 v[48:63], v[164:167], v[226:229], v[48:63]
	ds_read_b64_tr_b16 v[226:227], v187 offset:0x1400
	ds_read_b64_tr_b16 v[228:229], v187 offset:0x1c00
	v_mfma_f32_32x32x16_bf16 v[48:63], v[168:171], v[230:233], v[48:63]
	ds_read_b64_tr_b16 v[230:231], v187 offset:0x2400
	ds_read_b64_tr_b16 v[232:233], v187 offset:0x2c00
	v_mfma_f32_32x32x16_bf16 v[48:63], v[172:175], v[234:237], v[48:63]
	ds_read_b64_tr_b16 v[234:235], v187 offset:0x3400
	ds_read_b64_tr_b16 v[236:237], v187 offset:0x3c00
	s_waitcnt lgkmcnt(0)
	v_mfma_f32_32x32x16_bf16 v[32:47], v[160:163], v[222:225], v[32:47]
	ds_read_b64_tr_b16 v[222:223], v187 offset:0x600
	ds_read_b64_tr_b16 v[224:225], v187 offset:0xe00
	v_mfma_f32_32x32x16_bf16 v[32:47], v[164:167], v[226:229], v[32:47]
	ds_read_b64_tr_b16 v[226:227], v187 offset:0x1600
	ds_read_b64_tr_b16 v[228:229], v187 offset:0x1e00
	v_mfma_f32_32x32x16_bf16 v[32:47], v[168:171], v[230:233], v[32:47]
	ds_read_b64_tr_b16 v[230:231], v187 offset:0x2600
	ds_read_b64_tr_b16 v[232:233], v187 offset:0x2e00
	v_mfma_f32_32x32x16_bf16 v[32:47], v[172:175], v[234:237], v[32:47]
	ds_read_b64_tr_b16 v[234:235], v187 offset:0x3600
	ds_read_b64_tr_b16 v[236:237], v187 offset:0x3e00
	s_waitcnt lgkmcnt(0)
	v_mfma_f32_32x32x16_bf16 v[16:31], v[160:163], v[222:225], v[16:31]
	v_max_f32_e32 v160, v81, v81
	v_max_f32_e32 v161, v80, v80
	v_max_f32_e32 v160, v161, v160
	v_max3_f32 v160, v160, v82, v83
	v_max3_f32 v160, v160, v84, v85
	v_max3_f32 v160, v160, v86, v87
	v_max3_f32 v160, v160, v88, v89
	v_max3_f32 v160, v160, v90, v91
	v_max3_f32 v160, v160, v92, v93
	v_mfma_f32_32x32x16_bf16 v[16:31], v[164:167], v[226:229], v[16:31]
	v_max3_f32 v160, v160, v94, v95
	v_max3_f32 v160, v160, v64, v65
	v_max3_f32 v160, v160, v66, v67
	v_max3_f32 v160, v160, v68, v69
	v_max3_f32 v160, v160, v70, v71
	v_max3_f32 v160, v160, v72, v73
	v_max3_f32 v160, v160, v74, v75
	v_max3_f32 v160, v160, v76, v77
	v_mfma_f32_32x32x16_bf16 v[16:31], v[168:171], v[230:233], v[16:31]
	v_max3_f32 v160, v160, v78, v79
	v_mov_b32_e32 v161, v160
	s_nop 1
	v_permlane32_swap_b32_e32 v160, v161
	v_max_f32_e32 v161, v161, v161
	v_max_f32_e32 v160, v160, v160
	v_max_f32_e32 v160, v160, v161
	v_sub_f32_e32 v161, v160, v205
	v_cmp_ge_f32_e32 vcc, s4, v161
	v_max_f32_e32 v161, v205, v205
	v_max_f32_e32 v161, v161, v160
	v_mfma_f32_32x32x16_bf16 v[16:31], v[172:175], v[234:237], v[16:31]
	v_sub_f32_e32 v160, v205, v161
	v_mul_f32_e32 v160, 0x3e0293ee, v160
	v_exp_f32_e32 v160, v160
	s_cmp_eq_u64 vcc, exec
	s_cselect_b64 s[0:1], -1, 0
	s_cmp_ge_u32 s5, 0x2000
	s_cbranch_scc1 .Latt_nb_p0c
	s_waitcnt vmcnt(4)
	s_barrier
; __device__ __forceinline__ void partialSM(f32x16& p0, f32x16& p1, float& m_reg, float& mn, float& alpha) {
;     ...
;   float mnC = -mn * C;
;   for (int r = 0; r < 16; ++r) p0[r] = fmaf(p0[r], C, mnC); for (int r = 0; r < 16; ++r) p1[r] = fmaf(p1[r], C, mnC);
;   for (int r = 0; r < 16; ++r) p0[r] = __builtin_amdgcn_exp2f(p0[r]);
; }
; __device__ __forceinline__ void finishSM(f32x16& p0, f32x16& p1, float alpha, float& l_reg, bf16x8& pa0, bf16x8& pa1, bf16x8& pa2, bf16x8& pa3) {
;   for (int r = 0; r < 16; ++r) p1[r] = __builtin_amdgcn_exp2f(p1[r]);
;   float ps = 0; for (int r = 0; r < 16; ++r) ps += p0[r]; for (int r = 0; r < 16; ++r) ps += p1[r];
;   { auto rr = __builtin_amdgcn_permlane32_swap(__float_as_uint(ps), __float_as_uint(ps), false, false);
;     ps = __uint_as_float(rr[0]) + __uint_as_float(rr[1]); }
;   l_reg = l_reg * alpha + ps;
.Latt_nb_p0c:
	v_cndmask_b32_e64 v160, v160, 1.0, s[0:1]
	v_cmp_gt_f32_e32 vcc, 1.0, v160
	s_add_i32 m0, s5, s28
	s_add_i32 m0, m0, 0xc000
	s_nop 0
	global_load_lds_dwordx4 v128, s[6:7]
	s_add_i32 m0, s5, s28
	s_add_i32 m0, m0, 0xc400
	s_nop 0
	global_load_lds_dwordx4 v129, s[6:7]
	s_add_i32 m0, s5, s28
	s_add_i32 m0, m0, 0x0
	s_nop 0
	global_load_lds_dwordx4 v130, s[68:69]
	s_add_i32 m0, s5, s28
	s_add_i32 m0, m0, 0x400
	s_nop 0
	global_load_lds_dwordx4 v131, s[68:69]
	s_add_u32 s6, s6, 0x4000
	s_addc_u32 s7, s7, 0
	s_add_u32 s68, s68, 0x4000
	s_addc_u32 s69, s69, 0
	v_xor_b32_e32 v187, 0x10000, v187
	v_xor_b32_e32 v188, 0x10000, v188
	s_xor_b32 s28, s28, 0x10000
	s_xor_b32 s29, s29, 0x10000
	s_cbranch_vccz .LBB0_86
	s_and_saveexec_b64 s[46:47], s[38:39]
	ds_write_b32 v185, v160 offset:128
	s_or_b64 exec, exec, s[46:47]
	s_waitcnt lgkmcnt(0)
	v_add_u32_e32 v156, v184, v208
	ds_read_b128 v[144:147], v156 offset:224
	ds_read_b128 v[148:151], v156 offset:192
	ds_read_b128 v[152:155], v156 offset:160
	ds_read_b128 v[156:159], v156 offset:128
	s_waitcnt lgkmcnt(3)
	v_pk_mul_f32 v[12:13], v[12:13], v[144:145]
	s_waitcnt lgkmcnt(2)
	v_pk_mul_f32 v[8:9], v[8:9], v[148:149]
	s_waitcnt lgkmcnt(1)
	v_pk_mul_f32 v[4:5], v[4:5], v[152:153]
	v_pk_mul_f32 v[14:15], v[14:15], v[146:147]
	v_pk_mul_f32 v[10:11], v[10:11], v[150:151]
	v_pk_mul_f32 v[6:7], v[6:7], v[154:155]
	s_waitcnt lgkmcnt(0)
	v_pk_mul_f32 v[2:3], v[2:3], v[158:159]
	v_pk_mul_f32 v[0:1], v[0:1], v[156:157]
	v_pk_mul_f32 v[60:61], v[60:61], v[144:145]
	v_pk_mul_f32 v[56:57], v[56:57], v[148:149]
	v_pk_mul_f32 v[52:53], v[52:53], v[152:153]
	v_pk_mul_f32 v[62:63], v[62:63], v[146:147]
	v_pk_mul_f32 v[58:59], v[58:59], v[150:151]
	v_pk_mul_f32 v[54:55], v[54:55], v[154:155]
	v_pk_mul_f32 v[50:51], v[50:51], v[158:159]
	v_pk_mul_f32 v[48:49], v[48:49], v[156:157]
	v_pk_mul_f32 v[44:45], v[44:45], v[144:145]
	v_pk_mul_f32 v[40:41], v[40:41], v[148:149]
	v_pk_mul_f32 v[36:37], v[36:37], v[152:153]
	v_pk_mul_f32 v[46:47], v[46:47], v[146:147]
	v_pk_mul_f32 v[42:43], v[42:43], v[150:151]
	v_pk_mul_f32 v[38:39], v[38:39], v[154:155]
	v_pk_mul_f32 v[34:35], v[34:35], v[158:159]
	v_pk_mul_f32 v[32:33], v[32:33], v[156:157]
	v_pk_mul_f32 v[28:29], v[28:29], v[144:145]
	v_pk_mul_f32 v[24:25], v[24:25], v[148:149]
	v_pk_mul_f32 v[20:21], v[20:21], v[152:153]
	v_pk_mul_f32 v[30:31], v[30:31], v[146:147]
	v_pk_mul_f32 v[26:27], v[26:27], v[150:151]
	v_pk_mul_f32 v[22:23], v[22:23], v[154:155]
	v_pk_mul_f32 v[18:19], v[18:19], v[158:159]
	v_pk_mul_f32 v[16:17], v[16:17], v[156:157]
.LBB0_86:
	v_cndmask_b32_e64 v168, v161, v205, s[0:1]
	v_mul_f32_e32 v144, 0xbe0293ee, v168
	v_mov_b32_e32 v145, v144
	v_fmamk_f32 v80, v80, 0x3e0293ee, v144
	v_fmamk_f32 v81, v81, 0x3e0293ee, v144
	v_fmamk_f32 v82, v82, 0x3e0293ee, v144
	v_fmamk_f32 v83, v83, 0x3e0293ee, v144
	v_fmamk_f32 v84, v84, 0x3e0293ee, v144
	v_fmamk_f32 v85, v85, 0x3e0293ee, v144
	v_fmamk_f32 v86, v86, 0x3e0293ee, v144
	v_fmamk_f32 v87, v87, 0x3e0293ee, v144
	v_fmamk_f32 v88, v88, 0x3e0293ee, v144
	v_fmamk_f32 v89, v89, 0x3e0293ee, v144
	v_fmamk_f32 v90, v90, 0x3e0293ee, v144
	v_fmamk_f32 v91, v91, 0x3e0293ee, v144
	v_fmamk_f32 v92, v92, 0x3e0293ee, v144
	v_fmamk_f32 v93, v93, 0x3e0293ee, v144
	v_fmamk_f32 v94, v94, 0x3e0293ee, v144
	v_fmac_f32_e32 v145, 0x3e0293ee, v95
	v_exp_f32_e32 v161, v80
	v_exp_f32_e32 v175, v81
	v_exp_f32_e32 v162, v82
	v_exp_f32_e32 v205, v83
	v_exp_f32_e32 v174, v84
	v_exp_f32_e32 v214, v85
	v_exp_f32_e32 v163, v86
	v_exp_f32_e32 v173, v87
	v_exp_f32_e32 v164, v88
	v_exp_f32_e32 v171, v89
	v_exp_f32_e32 v165, v90
	v_exp_f32_e32 v172, v91
	v_exp_f32_e32 v166, v92
	v_exp_f32_e32 v169, v93
	v_exp_f32_e32 v167, v94
	v_exp_f32_e32 v170, v145
	v_pk_fma_f32 v[158:159], v[64:65], s[22:23], v[144:145] op_sel_hi:[1,0,0]
	v_add_f32_e32 v64, v202, v203
	v_fmac_f32_e32 v64, v201, v186
	v_add_f32_e32 v186, v206, v207
	s_mov_b64 s[0:1], 0x8000
	v_pk_fma_f32 v[156:157], v[66:67], s[22:23], v[144:145] op_sel_hi:[1,0,0]
	v_pk_fma_f32 v[152:153], v[68:69], s[22:23], v[144:145] op_sel_hi:[1,0,0]
	v_pk_fma_f32 v[148:149], v[70:71], s[22:23], v[144:145] op_sel_hi:[1,0,0]
	v_pk_fma_f32 v[146:147], v[72:73], s[22:23], v[144:145] op_sel_hi:[1,0,0]
	v_pk_fma_f32 v[154:155], v[74:75], s[22:23], v[144:145] op_sel_hi:[1,0,0]
	v_pk_fma_f32 v[150:151], v[76:77], s[22:23], v[144:145] op_sel_hi:[1,0,0]
	v_pk_fma_f32 v[144:145], v[78:79], s[22:23], v[144:145] op_sel_hi:[1,0,0]
	v_fmac_f32_e32 v186, v64, v204
	s_add_i32 s2, s2, 2
	v_lshl_add_u64 v[180:181], v[180:181], 0, s[0:1]
	s_and_b64 vcc, exec, s[42:43]
	s_waitcnt lgkmcnt(0)
	s_cmp_ge_u32 s5, 0x2000
	s_cbranch_scc0 .Latt_nb_p1b
	s_waitcnt vmcnt(4)
	s_barrier
.Latt_nb_p1b:
	s_cbranch_vccnz .LBB0_88
	v_mov_b32_e32 v201, v160
	s_branch .LBB0_76
